# v32: v31 + write-through stores in P0 rmsnorm, rwkv_prep tiles and mix_rwkv (fewer dirty L2 lines at the grid barriers)
# baseline (speedup 1.0000x reference)
.LBB0_19:
	global_load_dwordx4 v[12:15], v[2:3], off offset:-2048 nt
	global_load_dwordx4 v[16:19], v[2:3], off offset:-1024 nt
	global_load_dwordx4 v[20:23], v[2:3], off nt
	global_load_dwordx4 v[24:27], v[2:3], off offset:1024 nt
	v_lshl_add_u64 v[2:3], v[2:3], 0, s[8:9]
	global_load_dwordx4 v[100:103], v[2:3], off offset:-2048 nt
	global_load_dwordx4 v[104:107], v[2:3], off offset:-1024 nt
	global_load_dwordx4 v[108:111], v[2:3], off nt
	global_load_dwordx4 v[112:115], v[2:3], off offset:1024 nt
	v_lshl_add_u64 v[2:3], v[2:3], 0, s[8:9]
	global_load_dwordx4 v[116:119], v[2:3], off offset:-2048 nt
	global_load_dwordx4 v[120:123], v[2:3], off offset:-1024 nt
	global_load_dwordx4 v[124:127], v[2:3], off nt
	global_load_dwordx4 v[128:131], v[2:3], off offset:1024 nt
	v_lshl_add_u64 v[2:3], v[2:3], 0, s[8:9]
	global_load_dwordx4 v[132:135], v[2:3], off offset:-2048 nt
	global_load_dwordx4 v[136:139], v[2:3], off offset:-1024 nt
	global_load_dwordx4 v[140:143], v[2:3], off nt
	global_load_dwordx4 v[144:147], v[2:3], off offset:1024 nt
	v_lshl_add_u64 v[2:3], v[2:3], 0, s[8:9]
	global_load_dwordx4 v[168:171], v[2:3], off offset:-2048 nt
	global_load_dwordx4 v[172:175], v[2:3], off offset:-1024 nt
	global_load_dwordx4 v[176:179], v[2:3], off nt
	global_load_dwordx4 v[180:183], v[2:3], off offset:1024 nt
	v_lshl_add_u64 v[2:3], v[2:3], 0, s[8:9]
	global_load_dwordx4 v[184:187], v[2:3], off offset:-2048 nt
	global_load_dwordx4 v[188:191], v[2:3], off offset:-1024 nt
	global_load_dwordx4 v[192:195], v[2:3], off nt
	global_load_dwordx4 v[196:199], v[2:3], off offset:1024 nt
	v_lshl_add_u64 v[2:3], v[2:3], 0, s[8:9]
	global_load_dwordx4 v[200:203], v[2:3], off offset:-2048 nt
	global_load_dwordx4 v[204:207], v[2:3], off offset:-1024 nt
	global_load_dwordx4 v[208:211], v[2:3], off nt
	global_load_dwordx4 v[212:215], v[2:3], off offset:1024 nt
	v_lshl_add_u64 v[2:3], v[2:3], 0, s[8:9]
	global_load_dwordx4 v[216:219], v[2:3], off offset:-2048 nt
	global_load_dwordx4 v[220:223], v[2:3], off offset:-1024 nt
	global_load_dwordx4 v[224:227], v[2:3], off nt
	global_load_dwordx4 v[228:231], v[2:3], off offset:1024 nt
	v_lshl_add_u64 v[2:3], v[2:3], 0, s[8:9]
	s_mov_b32 s0, 0x800000
	s_waitcnt vmcnt(28)
	v_add_u32_e32 v0, s6, v0
	v_mov_b32_e32 v234, v13
	v_mov_b32_e32 v235, v17
	v_mov_b32_e32 v232, v12
	v_mov_b32_e32 v233, v16
	v_pk_mul_f32 v[234:235], v[234:235], v[234:235]
	s_nop 0
	v_pk_fma_f32 v[232:233], v[232:233], v[232:233], v[234:235]
	v_mov_b32_e32 v234, v14
	v_mov_b32_e32 v235, v18
	v_pk_fma_f32 v[232:233], v[234:235], v[234:235], v[232:233]
	v_mov_b32_e32 v234, v15
	v_mov_b32_e32 v235, v19
	v_pk_fma_f32 v[236:237], v[234:235], v[234:235], v[232:233]
	s_nop 0
	v_add_f32_e32 v236, v236, v237
	v_mov_b32_e32 v240, v21
	v_mov_b32_e32 v241, v25
	v_mov_b32_e32 v238, v20
	v_mov_b32_e32 v239, v24
	v_pk_mul_f32 v[240:241], v[240:241], v[240:241]
	s_nop 0
	v_pk_fma_f32 v[238:239], v[238:239], v[238:239], v[240:241]
	v_mov_b32_e32 v240, v22
	v_mov_b32_e32 v241, v26
	v_pk_fma_f32 v[238:239], v[240:241], v[240:241], v[238:239]
	v_mov_b32_e32 v240, v23
	v_mov_b32_e32 v241, v27
	v_pk_fma_f32 v[238:239], v[240:241], v[240:241], v[238:239]
	s_nop 0
	v_add_f32_e32 v236, v236, v238
	v_add_f32_e32 v236, v236, v239
	ds_bpermute_b32 v237, v6, v236
	s_waitcnt lgkmcnt(0)
	v_add_f32_e32 v236, v236, v237
	ds_bpermute_b32 v237, v7, v236
	s_waitcnt lgkmcnt(0)
	v_add_f32_e32 v236, v236, v237
	ds_bpermute_b32 v237, v8, v236
	s_waitcnt lgkmcnt(0)
	v_add_f32_e32 v236, v236, v237
	ds_bpermute_b32 v237, v9, v236
	s_waitcnt lgkmcnt(0)
	v_add_f32_e32 v236, v236, v237
	ds_bpermute_b32 v237, v10, v236
	s_waitcnt lgkmcnt(0)
	v_add_f32_e32 v236, v236, v237
	ds_bpermute_b32 v237, v11, v236
	s_waitcnt lgkmcnt(0)
	v_add_f32_e32 v236, v236, v237
	v_fmamk_f32 v236, v236, 0x3a800000, v1
	v_cmp_gt_f32_e32 vcc, s0, v236
	v_mul_f32_e32 v237, 0x4b800000, v236
	s_nop 0
	v_cndmask_b32_e32 v236, v236, v237, vcc
	v_rsq_f32_e32 v236, v236
	s_nop 0
	v_mul_f32_e32 v237, 0x45800000, v236
	v_cndmask_b32_e32 v236, v236, v237, vcc
	v_pk_mul_f32 v[12:13], v[12:13], v[236:237] op_sel_hi:[1,0]
	v_pk_mul_f32 v[14:15], v[14:15], v[236:237] op_sel_hi:[1,0]
	v_cvt_pk_bf16_f32 v12, v12, v13
	v_cvt_pk_bf16_f32 v13, v14, v15
	global_store_dwordx2 v[4:5], v[12:13], off sc0 sc1
	v_pk_mul_f32 v[16:17], v[16:17], v[236:237] op_sel_hi:[1,0]
	v_pk_mul_f32 v[18:19], v[18:19], v[236:237] op_sel_hi:[1,0]
	v_cvt_pk_bf16_f32 v16, v16, v17
	v_cvt_pk_bf16_f32 v17, v18, v19
	global_store_dwordx2 v[4:5], v[16:17], off offset:512 sc0 sc1
	v_pk_mul_f32 v[20:21], v[20:21], v[236:237] op_sel_hi:[1,0]
	v_pk_mul_f32 v[22:23], v[22:23], v[236:237] op_sel_hi:[1,0]
	v_cvt_pk_bf16_f32 v20, v20, v21
	v_cvt_pk_bf16_f32 v21, v22, v23
	global_store_dwordx2 v[4:5], v[20:21], off offset:1024 sc0 sc1
	v_pk_mul_f32 v[24:25], v[24:25], v[236:237] op_sel_hi:[1,0]
	v_pk_mul_f32 v[26:27], v[26:27], v[236:237] op_sel_hi:[1,0]
	v_cvt_pk_bf16_f32 v24, v24, v25
	v_cvt_pk_bf16_f32 v25, v26, v27
	global_store_dwordx2 v[4:5], v[24:25], off offset:1536 sc0 sc1
	v_lshl_add_u64 v[4:5], v[4:5], 0, s[10:11]
	s_waitcnt vmcnt(28)
	v_add_u32_e32 v0, s6, v0
	v_mov_b32_e32 v234, v101
	v_mov_b32_e32 v235, v105
	v_mov_b32_e32 v232, v100
	v_mov_b32_e32 v233, v104
	v_pk_mul_f32 v[234:235], v[234:235], v[234:235]
	s_nop 0
	v_pk_fma_f32 v[232:233], v[232:233], v[232:233], v[234:235]
	v_mov_b32_e32 v234, v102
	v_mov_b32_e32 v235, v106
	v_pk_fma_f32 v[232:233], v[234:235], v[234:235], v[232:233]
	v_mov_b32_e32 v234, v103
	v_mov_b32_e32 v235, v107
	v_pk_fma_f32 v[236:237], v[234:235], v[234:235], v[232:233]
	s_nop 0
	v_add_f32_e32 v236, v236, v237
	v_mov_b32_e32 v240, v109
	v_mov_b32_e32 v241, v113
	v_mov_b32_e32 v238, v108
	v_mov_b32_e32 v239, v112
	v_pk_mul_f32 v[240:241], v[240:241], v[240:241]
	s_nop 0
	v_pk_fma_f32 v[238:239], v[238:239], v[238:239], v[240:241]
	v_mov_b32_e32 v240, v110
	v_mov_b32_e32 v241, v114
	v_pk_fma_f32 v[238:239], v[240:241], v[240:241], v[238:239]
	v_mov_b32_e32 v240, v111
	v_mov_b32_e32 v241, v115
	v_pk_fma_f32 v[238:239], v[240:241], v[240:241], v[238:239]
	s_nop 0
	v_add_f32_e32 v236, v236, v238
	v_add_f32_e32 v236, v236, v239
	ds_bpermute_b32 v237, v6, v236
	s_waitcnt lgkmcnt(0)
	v_add_f32_e32 v236, v236, v237
	ds_bpermute_b32 v237, v7, v236
	s_waitcnt lgkmcnt(0)
	v_add_f32_e32 v236, v236, v237
	ds_bpermute_b32 v237, v8, v236
	s_waitcnt lgkmcnt(0)
	v_add_f32_e32 v236, v236, v237
	ds_bpermute_b32 v237, v9, v236
	s_waitcnt lgkmcnt(0)
	v_add_f32_e32 v236, v236, v237
	ds_bpermute_b32 v237, v10, v236
	s_waitcnt lgkmcnt(0)
	v_add_f32_e32 v236, v236, v237
	ds_bpermute_b32 v237, v11, v236
	s_waitcnt lgkmcnt(0)
	v_add_f32_e32 v236, v236, v237
	v_fmamk_f32 v236, v236, 0x3a800000, v1
	v_cmp_gt_f32_e32 vcc, s0, v236
	v_mul_f32_e32 v237, 0x4b800000, v236
	s_nop 0
	v_cndmask_b32_e32 v236, v236, v237, vcc
	v_rsq_f32_e32 v236, v236
	s_nop 0
	v_mul_f32_e32 v237, 0x45800000, v236
	v_cndmask_b32_e32 v236, v236, v237, vcc
	v_pk_mul_f32 v[100:101], v[100:101], v[236:237] op_sel_hi:[1,0]
	v_pk_mul_f32 v[102:103], v[102:103], v[236:237] op_sel_hi:[1,0]
	v_cvt_pk_bf16_f32 v100, v100, v101
	v_cvt_pk_bf16_f32 v101, v102, v103
	global_store_dwordx2 v[4:5], v[100:101], off sc0 sc1
	v_pk_mul_f32 v[104:105], v[104:105], v[236:237] op_sel_hi:[1,0]
	v_pk_mul_f32 v[106:107], v[106:107], v[236:237] op_sel_hi:[1,0]
	v_cvt_pk_bf16_f32 v104, v104, v105
	v_cvt_pk_bf16_f32 v105, v106, v107
	global_store_dwordx2 v[4:5], v[104:105], off offset:512 sc0 sc1
	v_pk_mul_f32 v[108:109], v[108:109], v[236:237] op_sel_hi:[1,0]
	v_pk_mul_f32 v[110:111], v[110:111], v[236:237] op_sel_hi:[1,0]
	v_cvt_pk_bf16_f32 v108, v108, v109
	v_cvt_pk_bf16_f32 v109, v110, v111
	global_store_dwordx2 v[4:5], v[108:109], off offset:1024 sc0 sc1
	v_pk_mul_f32 v[112:113], v[112:113], v[236:237] op_sel_hi:[1,0]
	v_pk_mul_f32 v[114:115], v[114:115], v[236:237] op_sel_hi:[1,0]
	v_cvt_pk_bf16_f32 v112, v112, v113
	v_cvt_pk_bf16_f32 v113, v114, v115
	global_store_dwordx2 v[4:5], v[112:113], off offset:1536 sc0 sc1
	v_lshl_add_u64 v[4:5], v[4:5], 0, s[10:11]
	s_waitcnt vmcnt(28)
	v_add_u32_e32 v0, s6, v0
	v_mov_b32_e32 v234, v117
	v_mov_b32_e32 v235, v121
	v_mov_b32_e32 v232, v116
	v_mov_b32_e32 v233, v120
	v_pk_mul_f32 v[234:235], v[234:235], v[234:235]
	s_nop 0
	v_pk_fma_f32 v[232:233], v[232:233], v[232:233], v[234:235]
	v_mov_b32_e32 v234, v118
	v_mov_b32_e32 v235, v122
	v_pk_fma_f32 v[232:233], v[234:235], v[234:235], v[232:233]
	v_mov_b32_e32 v234, v119
	v_mov_b32_e32 v235, v123
	v_pk_fma_f32 v[236:237], v[234:235], v[234:235], v[232:233]
	s_nop 0
	v_add_f32_e32 v236, v236, v237
	v_mov_b32_e32 v240, v125
	v_mov_b32_e32 v241, v129
	v_mov_b32_e32 v238, v124
	v_mov_b32_e32 v239, v128
	v_pk_mul_f32 v[240:241], v[240:241], v[240:241]
	s_nop 0
	v_pk_fma_f32 v[238:239], v[238:239], v[238:239], v[240:241]
	v_mov_b32_e32 v240, v126
	v_mov_b32_e32 v241, v130
	v_pk_fma_f32 v[238:239], v[240:241], v[240:241], v[238:239]
	v_mov_b32_e32 v240, v127
	v_mov_b32_e32 v241, v131
	v_pk_fma_f32 v[238:239], v[240:241], v[240:241], v[238:239]
	s_nop 0
	v_add_f32_e32 v236, v236, v238
	v_add_f32_e32 v236, v236, v239
	ds_bpermute_b32 v237, v6, v236
	s_waitcnt lgkmcnt(0)
	v_add_f32_e32 v236, v236, v237
	ds_bpermute_b32 v237, v7, v236
	s_waitcnt lgkmcnt(0)
	v_add_f32_e32 v236, v236, v237
	ds_bpermute_b32 v237, v8, v236
	s_waitcnt lgkmcnt(0)
	v_add_f32_e32 v236, v236, v237
	ds_bpermute_b32 v237, v9, v236
	s_waitcnt lgkmcnt(0)
	v_add_f32_e32 v236, v236, v237
	ds_bpermute_b32 v237, v10, v236
	s_waitcnt lgkmcnt(0)
	v_add_f32_e32 v236, v236, v237
	ds_bpermute_b32 v237, v11, v236
	s_waitcnt lgkmcnt(0)
	v_add_f32_e32 v236, v236, v237
	v_fmamk_f32 v236, v236, 0x3a800000, v1
	v_cmp_gt_f32_e32 vcc, s0, v236
	v_mul_f32_e32 v237, 0x4b800000, v236
	s_nop 0
	v_cndmask_b32_e32 v236, v236, v237, vcc
	v_rsq_f32_e32 v236, v236
	s_nop 0
	v_mul_f32_e32 v237, 0x45800000, v236
	v_cndmask_b32_e32 v236, v236, v237, vcc
	v_pk_mul_f32 v[116:117], v[116:117], v[236:237] op_sel_hi:[1,0]
	v_pk_mul_f32 v[118:119], v[118:119], v[236:237] op_sel_hi:[1,0]
	v_cvt_pk_bf16_f32 v116, v116, v117
	v_cvt_pk_bf16_f32 v117, v118, v119
	global_store_dwordx2 v[4:5], v[116:117], off sc0 sc1
	v_pk_mul_f32 v[120:121], v[120:121], v[236:237] op_sel_hi:[1,0]
	v_pk_mul_f32 v[122:123], v[122:123], v[236:237] op_sel_hi:[1,0]
	v_cvt_pk_bf16_f32 v120, v120, v121
	v_cvt_pk_bf16_f32 v121, v122, v123
	global_store_dwordx2 v[4:5], v[120:121], off offset:512 sc0 sc1
	v_pk_mul_f32 v[124:125], v[124:125], v[236:237] op_sel_hi:[1,0]
	v_pk_mul_f32 v[126:127], v[126:127], v[236:237] op_sel_hi:[1,0]
	v_cvt_pk_bf16_f32 v124, v124, v125
	v_cvt_pk_bf16_f32 v125, v126, v127
	global_store_dwordx2 v[4:5], v[124:125], off offset:1024 sc0 sc1
	v_pk_mul_f32 v[128:129], v[128:129], v[236:237] op_sel_hi:[1,0]
	v_pk_mul_f32 v[130:131], v[130:131], v[236:237] op_sel_hi:[1,0]
	v_cvt_pk_bf16_f32 v128, v128, v129
	v_cvt_pk_bf16_f32 v129, v130, v131
	global_store_dwordx2 v[4:5], v[128:129], off offset:1536 sc0 sc1
	v_lshl_add_u64 v[4:5], v[4:5], 0, s[10:11]
	s_waitcnt vmcnt(28)
	v_add_u32_e32 v0, s6, v0
	v_mov_b32_e32 v234, v133
	v_mov_b32_e32 v235, v137
	v_mov_b32_e32 v232, v132
	v_mov_b32_e32 v233, v136
	v_pk_mul_f32 v[234:235], v[234:235], v[234:235]
	s_nop 0
	v_pk_fma_f32 v[232:233], v[232:233], v[232:233], v[234:235]
	v_mov_b32_e32 v234, v134
	v_mov_b32_e32 v235, v138
	v_pk_fma_f32 v[232:233], v[234:235], v[234:235], v[232:233]
	v_mov_b32_e32 v234, v135
	v_mov_b32_e32 v235, v139
	v_pk_fma_f32 v[236:237], v[234:235], v[234:235], v[232:233]
	s_nop 0
	v_add_f32_e32 v236, v236, v237
	v_mov_b32_e32 v240, v141
	v_mov_b32_e32 v241, v145
	v_mov_b32_e32 v238, v140
	v_mov_b32_e32 v239, v144
	v_pk_mul_f32 v[240:241], v[240:241], v[240:241]
	s_nop 0
	v_pk_fma_f32 v[238:239], v[238:239], v[238:239], v[240:241]
	v_mov_b32_e32 v240, v142
	v_mov_b32_e32 v241, v146
	v_pk_fma_f32 v[238:239], v[240:241], v[240:241], v[238:239]
	v_mov_b32_e32 v240, v143
	v_mov_b32_e32 v241, v147
	v_pk_fma_f32 v[238:239], v[240:241], v[240:241], v[238:239]
	s_nop 0
	v_add_f32_e32 v236, v236, v238
	v_add_f32_e32 v236, v236, v239
	ds_bpermute_b32 v237, v6, v236
	s_waitcnt lgkmcnt(0)
	v_add_f32_e32 v236, v236, v237
	ds_bpermute_b32 v237, v7, v236
	s_waitcnt lgkmcnt(0)
	v_add_f32_e32 v236, v236, v237
	ds_bpermute_b32 v237, v8, v236
	s_waitcnt lgkmcnt(0)
	v_add_f32_e32 v236, v236, v237
	ds_bpermute_b32 v237, v9, v236
	s_waitcnt lgkmcnt(0)
	v_add_f32_e32 v236, v236, v237
	ds_bpermute_b32 v237, v10, v236
	s_waitcnt lgkmcnt(0)
	v_add_f32_e32 v236, v236, v237
	ds_bpermute_b32 v237, v11, v236
	s_waitcnt lgkmcnt(0)
	v_add_f32_e32 v236, v236, v237
	v_fmamk_f32 v236, v236, 0x3a800000, v1
	v_cmp_gt_f32_e32 vcc, s0, v236
	v_mul_f32_e32 v237, 0x4b800000, v236
	s_nop 0
	v_cndmask_b32_e32 v236, v236, v237, vcc
	v_rsq_f32_e32 v236, v236
	s_nop 0
	v_mul_f32_e32 v237, 0x45800000, v236
	v_cndmask_b32_e32 v236, v236, v237, vcc
	v_pk_mul_f32 v[132:133], v[132:133], v[236:237] op_sel_hi:[1,0]
	v_pk_mul_f32 v[134:135], v[134:135], v[236:237] op_sel_hi:[1,0]
	v_cvt_pk_bf16_f32 v132, v132, v133
	v_cvt_pk_bf16_f32 v133, v134, v135
	global_store_dwordx2 v[4:5], v[132:133], off sc0 sc1
	v_pk_mul_f32 v[136:137], v[136:137], v[236:237] op_sel_hi:[1,0]
	v_pk_mul_f32 v[138:139], v[138:139], v[236:237] op_sel_hi:[1,0]
	v_cvt_pk_bf16_f32 v136, v136, v137
	v_cvt_pk_bf16_f32 v137, v138, v139
	global_store_dwordx2 v[4:5], v[136:137], off offset:512 sc0 sc1
	v_pk_mul_f32 v[140:141], v[140:141], v[236:237] op_sel_hi:[1,0]
	v_pk_mul_f32 v[142:143], v[142:143], v[236:237] op_sel_hi:[1,0]
	v_cvt_pk_bf16_f32 v140, v140, v141
	v_cvt_pk_bf16_f32 v141, v142, v143
	global_store_dwordx2 v[4:5], v[140:141], off offset:1024 sc0 sc1
	v_pk_mul_f32 v[144:145], v[144:145], v[236:237] op_sel_hi:[1,0]
	v_pk_mul_f32 v[146:147], v[146:147], v[236:237] op_sel_hi:[1,0]
	v_cvt_pk_bf16_f32 v144, v144, v145
	v_cvt_pk_bf16_f32 v145, v146, v147
	global_store_dwordx2 v[4:5], v[144:145], off offset:1536 sc0 sc1
	v_lshl_add_u64 v[4:5], v[4:5], 0, s[10:11]
	s_waitcnt vmcnt(28)
	v_add_u32_e32 v0, s6, v0
	v_mov_b32_e32 v234, v169
	v_mov_b32_e32 v235, v173
	v_mov_b32_e32 v232, v168
	v_mov_b32_e32 v233, v172
	v_pk_mul_f32 v[234:235], v[234:235], v[234:235]
	s_nop 0
	v_pk_fma_f32 v[232:233], v[232:233], v[232:233], v[234:235]
	v_mov_b32_e32 v234, v170
	v_mov_b32_e32 v235, v174
	v_pk_fma_f32 v[232:233], v[234:235], v[234:235], v[232:233]
	v_mov_b32_e32 v234, v171
	v_mov_b32_e32 v235, v175
	v_pk_fma_f32 v[236:237], v[234:235], v[234:235], v[232:233]
	s_nop 0
	v_add_f32_e32 v236, v236, v237
	v_mov_b32_e32 v240, v177
	v_mov_b32_e32 v241, v181
	v_mov_b32_e32 v238, v176
	v_mov_b32_e32 v239, v180
	v_pk_mul_f32 v[240:241], v[240:241], v[240:241]
	s_nop 0
	v_pk_fma_f32 v[238:239], v[238:239], v[238:239], v[240:241]
	v_mov_b32_e32 v240, v178
	v_mov_b32_e32 v241, v182
	v_pk_fma_f32 v[238:239], v[240:241], v[240:241], v[238:239]
	v_mov_b32_e32 v240, v179
	v_mov_b32_e32 v241, v183
	v_pk_fma_f32 v[238:239], v[240:241], v[240:241], v[238:239]
	s_nop 0
	v_add_f32_e32 v236, v236, v238
	v_add_f32_e32 v236, v236, v239
	ds_bpermute_b32 v237, v6, v236
	s_waitcnt lgkmcnt(0)
	v_add_f32_e32 v236, v236, v237
	ds_bpermute_b32 v237, v7, v236
	s_waitcnt lgkmcnt(0)
	v_add_f32_e32 v236, v236, v237
	ds_bpermute_b32 v237, v8, v236
	s_waitcnt lgkmcnt(0)
	v_add_f32_e32 v236, v236, v237
	ds_bpermute_b32 v237, v9, v236
	s_waitcnt lgkmcnt(0)
	v_add_f32_e32 v236, v236, v237
	ds_bpermute_b32 v237, v10, v236
	s_waitcnt lgkmcnt(0)
	v_add_f32_e32 v236, v236, v237
	ds_bpermute_b32 v237, v11, v236
	s_waitcnt lgkmcnt(0)
	v_add_f32_e32 v236, v236, v237
	v_fmamk_f32 v236, v236, 0x3a800000, v1
	v_cmp_gt_f32_e32 vcc, s0, v236
	v_mul_f32_e32 v237, 0x4b800000, v236
	s_nop 0
	v_cndmask_b32_e32 v236, v236, v237, vcc
	v_rsq_f32_e32 v236, v236
	s_nop 0
	v_mul_f32_e32 v237, 0x45800000, v236
	v_cndmask_b32_e32 v236, v236, v237, vcc
	v_pk_mul_f32 v[168:169], v[168:169], v[236:237] op_sel_hi:[1,0]
	v_pk_mul_f32 v[170:171], v[170:171], v[236:237] op_sel_hi:[1,0]
	v_cvt_pk_bf16_f32 v168, v168, v169
	v_cvt_pk_bf16_f32 v169, v170, v171
	global_store_dwordx2 v[4:5], v[168:169], off sc0 sc1
	v_pk_mul_f32 v[172:173], v[172:173], v[236:237] op_sel_hi:[1,0]
	v_pk_mul_f32 v[174:175], v[174:175], v[236:237] op_sel_hi:[1,0]
	v_cvt_pk_bf16_f32 v172, v172, v173
	v_cvt_pk_bf16_f32 v173, v174, v175
	global_store_dwordx2 v[4:5], v[172:173], off offset:512 sc0 sc1
	v_pk_mul_f32 v[176:177], v[176:177], v[236:237] op_sel_hi:[1,0]
	v_pk_mul_f32 v[178:179], v[178:179], v[236:237] op_sel_hi:[1,0]
	v_cvt_pk_bf16_f32 v176, v176, v177
	v_cvt_pk_bf16_f32 v177, v178, v179
	global_store_dwordx2 v[4:5], v[176:177], off offset:1024 sc0 sc1
	v_pk_mul_f32 v[180:181], v[180:181], v[236:237] op_sel_hi:[1,0]
	v_pk_mul_f32 v[182:183], v[182:183], v[236:237] op_sel_hi:[1,0]
	v_cvt_pk_bf16_f32 v180, v180, v181
	v_cvt_pk_bf16_f32 v181, v182, v183
	global_store_dwordx2 v[4:5], v[180:181], off offset:1536 sc0 sc1
	v_lshl_add_u64 v[4:5], v[4:5], 0, s[10:11]
	s_waitcnt vmcnt(28)
	v_add_u32_e32 v0, s6, v0
	v_mov_b32_e32 v234, v185
	v_mov_b32_e32 v235, v189
	v_mov_b32_e32 v232, v184
	v_mov_b32_e32 v233, v188
	v_pk_mul_f32 v[234:235], v[234:235], v[234:235]
	s_nop 0
	v_pk_fma_f32 v[232:233], v[232:233], v[232:233], v[234:235]
	v_mov_b32_e32 v234, v186
	v_mov_b32_e32 v235, v190
	v_pk_fma_f32 v[232:233], v[234:235], v[234:235], v[232:233]
	v_mov_b32_e32 v234, v187
	v_mov_b32_e32 v235, v191
	v_pk_fma_f32 v[236:237], v[234:235], v[234:235], v[232:233]
	s_nop 0
	v_add_f32_e32 v236, v236, v237
	v_mov_b32_e32 v240, v193
	v_mov_b32_e32 v241, v197
	v_mov_b32_e32 v238, v192
	v_mov_b32_e32 v239, v196
	v_pk_mul_f32 v[240:241], v[240:241], v[240:241]
	s_nop 0
	v_pk_fma_f32 v[238:239], v[238:239], v[238:239], v[240:241]
	v_mov_b32_e32 v240, v194
	v_mov_b32_e32 v241, v198
	v_pk_fma_f32 v[238:239], v[240:241], v[240:241], v[238:239]
	v_mov_b32_e32 v240, v195
	v_mov_b32_e32 v241, v199
	v_pk_fma_f32 v[238:239], v[240:241], v[240:241], v[238:239]
	s_nop 0
	v_add_f32_e32 v236, v236, v238
	v_add_f32_e32 v236, v236, v239
	ds_bpermute_b32 v237, v6, v236
	s_waitcnt lgkmcnt(0)
	v_add_f32_e32 v236, v236, v237
	ds_bpermute_b32 v237, v7, v236
	s_waitcnt lgkmcnt(0)
	v_add_f32_e32 v236, v236, v237
	ds_bpermute_b32 v237, v8, v236
	s_waitcnt lgkmcnt(0)
	v_add_f32_e32 v236, v236, v237
	ds_bpermute_b32 v237, v9, v236
	s_waitcnt lgkmcnt(0)
	v_add_f32_e32 v236, v236, v237
	ds_bpermute_b32 v237, v10, v236
	s_waitcnt lgkmcnt(0)
	v_add_f32_e32 v236, v236, v237
	ds_bpermute_b32 v237, v11, v236
	s_waitcnt lgkmcnt(0)
	v_add_f32_e32 v236, v236, v237
	v_fmamk_f32 v236, v236, 0x3a800000, v1
	v_cmp_gt_f32_e32 vcc, s0, v236
	v_mul_f32_e32 v237, 0x4b800000, v236
	s_nop 0
	v_cndmask_b32_e32 v236, v236, v237, vcc
	v_rsq_f32_e32 v236, v236
	s_nop 0
	v_mul_f32_e32 v237, 0x45800000, v236
	v_cndmask_b32_e32 v236, v236, v237, vcc
	v_pk_mul_f32 v[184:185], v[184:185], v[236:237] op_sel_hi:[1,0]
	v_pk_mul_f32 v[186:187], v[186:187], v[236:237] op_sel_hi:[1,0]
	v_cvt_pk_bf16_f32 v184, v184, v185
	v_cvt_pk_bf16_f32 v185, v186, v187
	global_store_dwordx2 v[4:5], v[184:185], off sc0 sc1
	v_pk_mul_f32 v[188:189], v[188:189], v[236:237] op_sel_hi:[1,0]
	v_pk_mul_f32 v[190:191], v[190:191], v[236:237] op_sel_hi:[1,0]
	v_cvt_pk_bf16_f32 v188, v188, v189
	v_cvt_pk_bf16_f32 v189, v190, v191
	global_store_dwordx2 v[4:5], v[188:189], off offset:512 sc0 sc1
	v_pk_mul_f32 v[192:193], v[192:193], v[236:237] op_sel_hi:[1,0]
	v_pk_mul_f32 v[194:195], v[194:195], v[236:237] op_sel_hi:[1,0]
	v_cvt_pk_bf16_f32 v192, v192, v193
	v_cvt_pk_bf16_f32 v193, v194, v195
	global_store_dwordx2 v[4:5], v[192:193], off offset:1024 sc0 sc1
	v_pk_mul_f32 v[196:197], v[196:197], v[236:237] op_sel_hi:[1,0]
	v_pk_mul_f32 v[198:199], v[198:199], v[236:237] op_sel_hi:[1,0]
	v_cvt_pk_bf16_f32 v196, v196, v197
	v_cvt_pk_bf16_f32 v197, v198, v199
	global_store_dwordx2 v[4:5], v[196:197], off offset:1536 sc0 sc1
	v_lshl_add_u64 v[4:5], v[4:5], 0, s[10:11]
	s_waitcnt vmcnt(28)
	v_add_u32_e32 v0, s6, v0
	v_mov_b32_e32 v234, v201
	v_mov_b32_e32 v235, v205
	v_mov_b32_e32 v232, v200
	v_mov_b32_e32 v233, v204
	v_pk_mul_f32 v[234:235], v[234:235], v[234:235]
	s_nop 0
	v_pk_fma_f32 v[232:233], v[232:233], v[232:233], v[234:235]
	v_mov_b32_e32 v234, v202
	v_mov_b32_e32 v235, v206
	v_pk_fma_f32 v[232:233], v[234:235], v[234:235], v[232:233]
	v_mov_b32_e32 v234, v203
	v_mov_b32_e32 v235, v207
	v_pk_fma_f32 v[236:237], v[234:235], v[234:235], v[232:233]
	s_nop 0
	v_add_f32_e32 v236, v236, v237
	v_mov_b32_e32 v240, v209
	v_mov_b32_e32 v241, v213
	v_mov_b32_e32 v238, v208
	v_mov_b32_e32 v239, v212
	v_pk_mul_f32 v[240:241], v[240:241], v[240:241]
	s_nop 0
	v_pk_fma_f32 v[238:239], v[238:239], v[238:239], v[240:241]
	v_mov_b32_e32 v240, v210
	v_mov_b32_e32 v241, v214
	v_pk_fma_f32 v[238:239], v[240:241], v[240:241], v[238:239]
	v_mov_b32_e32 v240, v211
	v_mov_b32_e32 v241, v215
	v_pk_fma_f32 v[238:239], v[240:241], v[240:241], v[238:239]
	s_nop 0
	v_add_f32_e32 v236, v236, v238
	v_add_f32_e32 v236, v236, v239
	ds_bpermute_b32 v237, v6, v236
	s_waitcnt lgkmcnt(0)
	v_add_f32_e32 v236, v236, v237
	ds_bpermute_b32 v237, v7, v236
	s_waitcnt lgkmcnt(0)
	v_add_f32_e32 v236, v236, v237
	ds_bpermute_b32 v237, v8, v236
	s_waitcnt lgkmcnt(0)
	v_add_f32_e32 v236, v236, v237
	ds_bpermute_b32 v237, v9, v236
	s_waitcnt lgkmcnt(0)
	v_add_f32_e32 v236, v236, v237
	ds_bpermute_b32 v237, v10, v236
	s_waitcnt lgkmcnt(0)
	v_add_f32_e32 v236, v236, v237
	ds_bpermute_b32 v237, v11, v236
	s_waitcnt lgkmcnt(0)
	v_add_f32_e32 v236, v236, v237
	v_fmamk_f32 v236, v236, 0x3a800000, v1
	v_cmp_gt_f32_e32 vcc, s0, v236
	v_mul_f32_e32 v237, 0x4b800000, v236
	s_nop 0
	v_cndmask_b32_e32 v236, v236, v237, vcc
	v_rsq_f32_e32 v236, v236
	s_nop 0
	v_mul_f32_e32 v237, 0x45800000, v236
	v_cndmask_b32_e32 v236, v236, v237, vcc
	v_pk_mul_f32 v[200:201], v[200:201], v[236:237] op_sel_hi:[1,0]
	v_pk_mul_f32 v[202:203], v[202:203], v[236:237] op_sel_hi:[1,0]
	v_cvt_pk_bf16_f32 v200, v200, v201
	v_cvt_pk_bf16_f32 v201, v202, v203
	global_store_dwordx2 v[4:5], v[200:201], off sc0 sc1
	v_pk_mul_f32 v[204:205], v[204:205], v[236:237] op_sel_hi:[1,0]
	v_pk_mul_f32 v[206:207], v[206:207], v[236:237] op_sel_hi:[1,0]
	v_cvt_pk_bf16_f32 v204, v204, v205
	v_cvt_pk_bf16_f32 v205, v206, v207
	global_store_dwordx2 v[4:5], v[204:205], off offset:512 sc0 sc1
	v_pk_mul_f32 v[208:209], v[208:209], v[236:237] op_sel_hi:[1,0]
	v_pk_mul_f32 v[210:211], v[210:211], v[236:237] op_sel_hi:[1,0]
	v_cvt_pk_bf16_f32 v208, v208, v209
	v_cvt_pk_bf16_f32 v209, v210, v211
	global_store_dwordx2 v[4:5], v[208:209], off offset:1024 sc0 sc1
	v_pk_mul_f32 v[212:213], v[212:213], v[236:237] op_sel_hi:[1,0]
	v_pk_mul_f32 v[214:215], v[214:215], v[236:237] op_sel_hi:[1,0]
	v_cvt_pk_bf16_f32 v212, v212, v213
	v_cvt_pk_bf16_f32 v213, v214, v215
	global_store_dwordx2 v[4:5], v[212:213], off offset:1536 sc0 sc1
	v_lshl_add_u64 v[4:5], v[4:5], 0, s[10:11]
	s_waitcnt vmcnt(28)
	v_add_u32_e32 v0, s6, v0
	v_mov_b32_e32 v234, v217
	v_mov_b32_e32 v235, v221
	v_mov_b32_e32 v232, v216
	v_mov_b32_e32 v233, v220
	v_pk_mul_f32 v[234:235], v[234:235], v[234:235]
	s_nop 0
	v_pk_fma_f32 v[232:233], v[232:233], v[232:233], v[234:235]
	v_mov_b32_e32 v234, v218
	v_mov_b32_e32 v235, v222
	v_pk_fma_f32 v[232:233], v[234:235], v[234:235], v[232:233]
	v_mov_b32_e32 v234, v219
	v_mov_b32_e32 v235, v223
	v_pk_fma_f32 v[236:237], v[234:235], v[234:235], v[232:233]
	s_nop 0
	v_add_f32_e32 v236, v236, v237
	v_mov_b32_e32 v240, v225
	v_mov_b32_e32 v241, v229
	v_mov_b32_e32 v238, v224
	v_mov_b32_e32 v239, v228
	v_pk_mul_f32 v[240:241], v[240:241], v[240:241]
	s_nop 0
	v_pk_fma_f32 v[238:239], v[238:239], v[238:239], v[240:241]
	v_mov_b32_e32 v240, v226
	v_mov_b32_e32 v241, v230
	v_pk_fma_f32 v[238:239], v[240:241], v[240:241], v[238:239]
	v_mov_b32_e32 v240, v227
	v_mov_b32_e32 v241, v231
	v_pk_fma_f32 v[238:239], v[240:241], v[240:241], v[238:239]
	s_nop 0
	v_add_f32_e32 v236, v236, v238
	v_add_f32_e32 v236, v236, v239
	ds_bpermute_b32 v237, v6, v236
	s_waitcnt lgkmcnt(0)
	v_add_f32_e32 v236, v236, v237
	ds_bpermute_b32 v237, v7, v236
	s_waitcnt lgkmcnt(0)
	v_add_f32_e32 v236, v236, v237
	ds_bpermute_b32 v237, v8, v236
	s_waitcnt lgkmcnt(0)
	v_add_f32_e32 v236, v236, v237
	ds_bpermute_b32 v237, v9, v236
	s_waitcnt lgkmcnt(0)
	v_add_f32_e32 v236, v236, v237
	ds_bpermute_b32 v237, v10, v236
	s_waitcnt lgkmcnt(0)
	v_add_f32_e32 v236, v236, v237
	ds_bpermute_b32 v237, v11, v236
	s_waitcnt lgkmcnt(0)
	v_add_f32_e32 v236, v236, v237
	v_fmamk_f32 v236, v236, 0x3a800000, v1
	v_cmp_gt_f32_e32 vcc, s0, v236
	v_mul_f32_e32 v237, 0x4b800000, v236
	s_nop 0
	v_cndmask_b32_e32 v236, v236, v237, vcc
	v_rsq_f32_e32 v236, v236
	s_nop 0
	v_mul_f32_e32 v237, 0x45800000, v236
	v_cndmask_b32_e32 v236, v236, v237, vcc
	v_pk_mul_f32 v[216:217], v[216:217], v[236:237] op_sel_hi:[1,0]
	v_pk_mul_f32 v[218:219], v[218:219], v[236:237] op_sel_hi:[1,0]
	v_cvt_pk_bf16_f32 v216, v216, v217
	v_cvt_pk_bf16_f32 v217, v218, v219
	global_store_dwordx2 v[4:5], v[216:217], off sc0 sc1
	v_pk_mul_f32 v[220:221], v[220:221], v[236:237] op_sel_hi:[1,0]
	v_pk_mul_f32 v[222:223], v[222:223], v[236:237] op_sel_hi:[1,0]
	v_cvt_pk_bf16_f32 v220, v220, v221
	v_cvt_pk_bf16_f32 v221, v222, v223
	global_store_dwordx2 v[4:5], v[220:221], off offset:512 sc0 sc1
	v_pk_mul_f32 v[224:225], v[224:225], v[236:237] op_sel_hi:[1,0]
	v_pk_mul_f32 v[226:227], v[226:227], v[236:237] op_sel_hi:[1,0]
	v_cvt_pk_bf16_f32 v224, v224, v225
	v_cvt_pk_bf16_f32 v225, v226, v227
	global_store_dwordx2 v[4:5], v[224:225], off offset:1024 sc0 sc1
	v_pk_mul_f32 v[228:229], v[228:229], v[236:237] op_sel_hi:[1,0]
	v_pk_mul_f32 v[230:231], v[230:231], v[236:237] op_sel_hi:[1,0]
	v_cvt_pk_bf16_f32 v228, v228, v229
	v_cvt_pk_bf16_f32 v229, v230, v231
	global_store_dwordx2 v[4:5], v[228:229], off offset:1536 sc0 sc1
	v_lshl_add_u64 v[4:5], v[4:5], 0, s[10:11]
	s_mov_b64 s[28:29], exec

.LBB0_520:
	v_readlane_b32 s12, v255, 29
	v_lshlrev_b64 v[18:19], 2, v[18:19]
	v_readlane_b32 s16, v255, 33
	v_readlane_b32 s17, v255, 34
	v_readlane_b32 s13, v255, 30
	v_readlane_b32 s14, v255, 31
	v_lshl_add_u64 v[18:19], v[16:17], 0, v[18:19]
	v_readlane_b32 s15, v255, 32
	v_readlane_b32 s18, v255, 35
	v_readlane_b32 s19, v255, 36
	v_readlane_b32 s20, v255, 37
	v_readlane_b32 s21, v255, 38
	v_readlane_b32 s22, v255, 39
	v_readlane_b32 s23, v255, 40
	v_readlane_b32 s24, v255, 41
	v_readlane_b32 s25, v255, 42
	v_readlane_b32 s26, v255, 43
	v_readlane_b32 s27, v255, 44
	s_mov_b32 s5, 0
	s_mov_b32 s4, 0x1000
	v_lshl_add_u64 v[128:129], v[18:19], 0, s[4:5]
	s_mov_b32 s4, 0x5000
	v_lshl_add_u64 v[130:131], v[18:19], 0, s[4:5]
	s_mov_b32 s4, 0x9000
	v_lshl_add_u64 v[132:133], v[18:19], 0, s[4:5]
	s_mov_b32 s4, 0xd000
	v_lshl_add_u64 v[134:135], v[18:19], 0, s[4:5]
	s_waitcnt vmcnt(0)
	v_mul_f32_e32 v87, 0xbfb8aa3b, v86
	v_fmamk_f32 v88, v0, 0xbfb8aa3b, v87
	v_fmamk_f32 v89, v1, 0xbfb8aa3b, v87
	v_fmamk_f32 v90, v2, 0xbfb8aa3b, v87
	v_fmamk_f32 v91, v3, 0xbfb8aa3b, v87
	v_exp_f32_e32 v88, v88
	v_exp_f32_e32 v89, v89
	v_exp_f32_e32 v90, v90
	v_exp_f32_e32 v91, v91
	v_add_f32_e32 v88, 1.0, v88
	v_add_f32_e32 v89, 1.0, v89
	v_add_f32_e32 v90, 1.0, v90
	v_add_f32_e32 v91, 1.0, v91
	v_rcp_f32_e32 v88, v88
	v_rcp_f32_e32 v89, v89
	v_rcp_f32_e32 v90, v90
	v_rcp_f32_e32 v91, v91
	v_mul_f32_e32 v88, 0xbf60028a, v88
	v_mul_f32_e32 v89, 0xbf60028a, v89
	v_mul_f32_e32 v90, 0xbf60028a, v90
	v_mul_f32_e32 v91, 0xbf60028a, v91
	v_exp_f32_e32 v88, v88
	v_exp_f32_e32 v89, v89
	v_exp_f32_e32 v90, v90
	v_exp_f32_e32 v91, v91
	global_store_dword v[128:129], v88, off offset:-4096 sc0 sc1 nt
	global_store_dword v[128:129], v89, off offset:-2048 sc0 sc1 nt
	global_store_dword v[128:129], v90, off sc0 sc1 nt
	global_store_dword v[128:129], v91, off offset:2048 sc0 sc1 nt
	v_fmamk_f32 v88, v4, 0xbfb8aa3b, v87
	v_fmamk_f32 v89, v5, 0xbfb8aa3b, v87
	v_fmamk_f32 v90, v6, 0xbfb8aa3b, v87
	v_fmamk_f32 v91, v7, 0xbfb8aa3b, v87
	v_exp_f32_e32 v88, v88
	v_exp_f32_e32 v89, v89
	v_exp_f32_e32 v90, v90
	v_exp_f32_e32 v91, v91
	v_add_f32_e32 v88, 1.0, v88
	v_add_f32_e32 v89, 1.0, v89
	v_add_f32_e32 v90, 1.0, v90
	v_add_f32_e32 v91, 1.0, v91
	v_rcp_f32_e32 v88, v88
	v_rcp_f32_e32 v89, v89
	v_rcp_f32_e32 v90, v90
	v_rcp_f32_e32 v91, v91
	v_mul_f32_e32 v88, 0xbf60028a, v88
	v_mul_f32_e32 v89, 0xbf60028a, v89
	v_mul_f32_e32 v90, 0xbf60028a, v90
	v_mul_f32_e32 v91, 0xbf60028a, v91
	v_exp_f32_e32 v88, v88
	v_exp_f32_e32 v89, v89
	v_exp_f32_e32 v90, v90
	v_exp_f32_e32 v91, v91
	global_store_dword v[130:131], v88, off offset:-4096 sc0 sc1 nt
	global_store_dword v[130:131], v89, off offset:-2048 sc0 sc1 nt
	global_store_dword v[130:131], v90, off sc0 sc1 nt
	global_store_dword v[130:131], v91, off offset:2048 sc0 sc1 nt
	v_fmamk_f32 v88, v8, 0xbfb8aa3b, v87
	v_fmamk_f32 v89, v9, 0xbfb8aa3b, v87
	v_fmamk_f32 v90, v10, 0xbfb8aa3b, v87
	v_fmamk_f32 v91, v11, 0xbfb8aa3b, v87
	v_exp_f32_e32 v88, v88
	v_exp_f32_e32 v89, v89
	v_exp_f32_e32 v90, v90
	v_exp_f32_e32 v91, v91
	v_add_f32_e32 v88, 1.0, v88
	v_add_f32_e32 v89, 1.0, v89
	v_add_f32_e32 v90, 1.0, v90
	v_add_f32_e32 v91, 1.0, v91
	v_rcp_f32_e32 v88, v88
	v_rcp_f32_e32 v89, v89
	v_rcp_f32_e32 v90, v90
	v_rcp_f32_e32 v91, v91
	v_mul_f32_e32 v88, 0xbf60028a, v88
	v_mul_f32_e32 v89, 0xbf60028a, v89
	v_mul_f32_e32 v90, 0xbf60028a, v90
	v_mul_f32_e32 v91, 0xbf60028a, v91
	v_exp_f32_e32 v88, v88
	v_exp_f32_e32 v89, v89
	v_exp_f32_e32 v90, v90
	v_exp_f32_e32 v91, v91
	global_store_dword v[132:133], v88, off offset:-4096 sc0 sc1 nt
	global_store_dword v[132:133], v89, off offset:-2048 sc0 sc1 nt
	global_store_dword v[132:133], v90, off sc0 sc1 nt
	global_store_dword v[132:133], v91, off offset:2048 sc0 sc1 nt
	v_fmamk_f32 v88, v12, 0xbfb8aa3b, v87
	v_fmamk_f32 v89, v13, 0xbfb8aa3b, v87
	v_fmamk_f32 v90, v14, 0xbfb8aa3b, v87
	v_fmamk_f32 v91, v15, 0xbfb8aa3b, v87
	v_exp_f32_e32 v88, v88
	v_exp_f32_e32 v89, v89
	v_exp_f32_e32 v90, v90
	v_exp_f32_e32 v91, v91
	v_add_f32_e32 v88, 1.0, v88
	v_add_f32_e32 v89, 1.0, v89
	v_add_f32_e32 v90, 1.0, v90
	v_add_f32_e32 v91, 1.0, v91
	v_rcp_f32_e32 v88, v88
	v_rcp_f32_e32 v89, v89
	v_rcp_f32_e32 v90, v90
	v_rcp_f32_e32 v91, v91
	v_mul_f32_e32 v88, 0xbf60028a, v88
	v_mul_f32_e32 v89, 0xbf60028a, v89
	v_mul_f32_e32 v90, 0xbf60028a, v90
	v_mul_f32_e32 v91, 0xbf60028a, v91
	v_exp_f32_e32 v88, v88
	v_exp_f32_e32 v89, v89
	v_exp_f32_e32 v90, v90
	v_exp_f32_e32 v91, v91
	global_store_dword v[134:135], v88, off offset:-4096 sc0 sc1 nt
	global_store_dword v[134:135], v89, off offset:-2048 sc0 sc1 nt
	global_store_dword v[134:135], v90, off sc0 sc1 nt
	global_store_dword v[134:135], v91, off offset:2048 sc0 sc1 nt
	s_branch .LBB0_516

.Lprep_noload:
	v_lshlrev_b32_e32 v60, 16, v28
	v_and_b32_e32 v61, 0xffff0000, v28
	v_lshlrev_b32_e32 v28, 16, v29
	v_and_b32_e32 v29, 0xffff0000, v29
	v_lshlrev_b32_e32 v62, 16, v30
	v_and_b32_e32 v63, 0xffff0000, v30
	v_lshlrev_b32_e32 v64, 16, v31
	v_and_b32_e32 v65, 0xffff0000, v31
	v_lshlrev_b32_e32 v30, 16, v20
	v_and_b32_e32 v31, 0xffff0000, v20
	v_lshlrev_b32_e32 v20, 16, v21
	v_and_b32_e32 v21, 0xffff0000, v21
	v_lshlrev_b32_e32 v66, 16, v22
	v_and_b32_e32 v67, 0xffff0000, v22
	v_pk_add_f32 v[30:31], v[30:31], v[60:61] neg_lo:[0,1] neg_hi:[0,1]
	v_pk_add_f32 v[20:21], v[20:21], v[28:29] neg_lo:[0,1] neg_hi:[0,1]
	v_lshlrev_b32_e32 v22, 16, v23
	v_and_b32_e32 v23, 0xffff0000, v23
	v_pk_fma_f32 v[36:37], v[30:31], v[36:37], v[60:61]
	v_pk_fma_f32 v[30:31], v[20:21], v[38:39], v[28:29]
	v_pk_add_f32 v[20:21], v[66:67], v[62:63] neg_lo:[0,1] neg_hi:[0,1]
	v_lshlrev_b32_e32 v28, 16, v4
	v_pk_fma_f32 v[32:33], v[20:21], v[32:33], v[62:63]
	v_pk_add_f32 v[20:21], v[22:23], v[64:65] neg_lo:[0,1] neg_hi:[0,1]
	v_and_b32_e32 v29, 0xffff0000, v4
	v_pk_fma_f32 v[68:69], v[20:21], v[34:35], v[64:65]
	v_lshlrev_b32_e32 v20, 16, v8
	v_and_b32_e32 v21, 0xffff0000, v8
	v_lshlrev_b32_e32 v8, 16, v9
	v_and_b32_e32 v9, 0xffff0000, v9
	v_lshlrev_b32_e32 v4, 16, v5
	v_and_b32_e32 v5, 0xffff0000, v5
	v_lshlrev_b32_e32 v22, 16, v10
	v_and_b32_e32 v23, 0xffff0000, v10
	v_lshlrev_b32_e32 v34, 16, v6
	v_and_b32_e32 v35, 0xffff0000, v6
	v_pk_add_f32 v[4:5], v[4:5], v[8:9] neg_lo:[0,1] neg_hi:[0,1]
	v_lshlrev_b32_e32 v10, 16, v11
	v_and_b32_e32 v11, 0xffff0000, v11
	v_lshlrev_b32_e32 v6, 16, v7
	v_and_b32_e32 v7, 0xffff0000, v7
	v_pk_fma_f32 v[18:19], v[4:5], v[18:19], v[8:9]
	v_pk_add_f32 v[4:5], v[34:35], v[22:23] neg_lo:[0,1] neg_hi:[0,1]
	s_movk_i32 s4, 0x410
	v_pk_fma_f32 v[12:13], v[4:5], v[12:13], v[22:23]
	v_pk_add_f32 v[4:5], v[6:7], v[10:11] neg_lo:[0,1] neg_hi:[0,1]
	v_pk_add_f32 v[28:29], v[28:29], v[20:21] neg_lo:[0,1] neg_hi:[0,1]
	v_pk_fma_f32 v[14:15], v[4:5], v[14:15], v[10:11]
	v_mad_u64_u32 v[4:5], s[4:5], v58, s4, v[42:43]
	ds_read_b128 v[58:61], v4 offset:9216
	v_pk_fma_f32 v[16:17], v[28:29], v[16:17], v[20:21]
	v_lshlrev_b32_e32 v22, 16, v26
	v_and_b32_e32 v23, 0xffff0000, v26
	v_lshlrev_b32_e32 v20, 16, v27
	s_waitcnt lgkmcnt(0)
	v_lshlrev_b32_e32 v6, 16, v58
	v_and_b32_e32 v7, 0xffff0000, v58
	v_lshlrev_b32_e32 v8, 16, v59
	v_and_b32_e32 v9, 0xffff0000, v59
	v_lshlrev_b32_e32 v10, 16, v60
	v_and_b32_e32 v11, 0xffff0000, v60
	v_lshlrev_b32_e32 v4, 16, v61
	v_and_b32_e32 v5, 0xffff0000, v61
	v_mov_b32_e32 v58, v200
	v_mov_b32_e32 v59, v201
	v_mov_b32_e32 v60, v202
	v_mov_b32_e32 v61, v203
	v_mov_b32_e32 v62, v204
	v_mov_b32_e32 v63, v205
	v_mov_b32_e32 v64, v206
	v_mov_b32_e32 v65, v207
	v_and_b32_e32 v21, 0xffff0000, v27
	v_pk_add_f32 v[26:27], v[10:11], -1.0 op_sel_hi:[1,0]
	s_mov_b32 s4, 0xf800000
	v_lshlrev_b32_e32 v28, 16, v24
	v_and_b32_e32 v29, 0xffff0000, v24
	v_lshlrev_b32_e32 v24, 16, v25
	v_and_b32_e32 v25, 0xffff0000, v25
	v_ashrrev_i32_e32 v57, 31, v56
	s_addk_i32 s6, 0x100
	s_cmpk_lg_i32 s6, 0x800
	v_pk_mul_f32 v[66:67], v[68:69], v[60:61]
	v_pk_mul_f32 v[38:39], v[32:33], v[58:59]
	v_mov_b32_e32 v80, v208
	v_mov_b32_e32 v81, v209
	v_mov_b32_e32 v82, v210
	v_mov_b32_e32 v83, v211
	v_mov_b32_e32 v58, v212
	v_mov_b32_e32 v59, v213
	v_mov_b32_e32 v60, v214
	v_mov_b32_e32 v61, v215
	v_pk_mul_f32 v[64:65], v[30:31], v[64:65]
	v_pk_mul_f32 v[70:71], v[38:39], v[38:39]
	v_pk_mul_f32 v[34:35], v[66:67], v[66:67]
	v_pk_fma_f32 v[26:27], v[26:27], v[80:81], 1.0 op_sel_hi:[1,1,0]
	s_nop 0
	v_pk_mul_f32 v[26:27], v[32:33], v[26:27]
	v_pk_add_f32 v[32:33], v[8:9], -1.0 op_sel_hi:[1,0]
	v_pk_mul_f32 v[80:81], v[64:65], v[64:65]
	v_pk_fma_f32 v[32:33], v[32:33], v[60:61], 1.0 op_sel_hi:[1,1,0]
	v_pk_mul_f32 v[60:61], v[36:37], v[62:63]
	v_pk_mul_f32 v[30:31], v[30:31], v[32:33]
	v_pk_add_f32 v[32:33], v[6:7], -1.0 op_sel_hi:[1,0]
	v_pk_mul_f32 v[62:63], v[60:61], v[60:61]
	v_pk_fma_f32 v[32:33], v[32:33], v[58:59], 1.0 op_sel_hi:[1,1,0]
	s_nop 0
	v_pk_mul_f32 v[32:33], v[36:37], v[32:33]
	v_add_f32_e32 v36, v62, v63
	v_add_f32_e32 v36, v36, v80
	v_add_f32_e32 v36, v36, v81
	v_add_f32_e32 v36, v36, v70
	v_add_f32_e32 v36, v36, v71
	v_add_f32_e32 v34, v36, v34
	v_add_f32_e32 v34, v34, v35
	ds_bpermute_b32 v35, v77, v34
	v_lshlrev_b32_e32 v70, 16, v0
	v_and_b32_e32 v71, 0xffff0000, v0
	v_lshlrev_b32_e32 v0, 16, v1
	v_and_b32_e32 v1, 0xffff0000, v1
	s_waitcnt lgkmcnt(0)
	v_add_f32_e32 v34, v34, v35
	ds_bpermute_b32 v35, v78, v34
	v_pk_add_f32 v[0:1], v[0:1], v[24:25] neg_lo:[0,1] neg_hi:[0,1]
	v_pk_add_f32 v[70:71], v[70:71], v[28:29] neg_lo:[0,1] neg_hi:[0,1]
	s_waitcnt lgkmcnt(0)
	v_add_f32_e32 v34, v34, v35
	ds_bpermute_b32 v35, v79, v34
	s_waitcnt lgkmcnt(0)
	v_add_f32_e32 v34, v34, v35
	v_cmp_gt_f32_e32 vcc, s4, v34
	v_mul_f32_e32 v35, 0x4f800000, v34
	s_nop 0
	v_cndmask_b32_e32 v34, v34, v35, vcc
	v_sqrt_f32_e32 v35, v34
	s_nop 0
	v_add_u32_e32 v36, -1, v35
	v_fma_f32 v37, -v36, v35, v34
	v_cmp_ge_f32_e64 s[4:5], 0, v37
	v_add_u32_e32 v37, 1, v35
	s_nop 0
	v_cndmask_b32_e64 v36, v35, v36, s[4:5]
	v_fma_f32 v35, -v37, v35, v34
	v_cmp_lt_f32_e64 s[4:5], 0, v35
	s_nop 1
	v_cndmask_b32_e64 v35, v36, v37, s[4:5]
	v_mul_f32_e32 v36, 0x37800000, v35
	v_cndmask_b32_e32 v35, v35, v36, vcc
	v_cmp_class_f32_e32 vcc, v34, v73
	s_nop 1
	v_cndmask_b32_e32 v34, v35, v34, vcc
	v_max_f32_e32 v34, 0x2b8cbccc, v34
	v_div_scale_f32 v35, s[4:5], v34, v34, 1.0
	v_rcp_f32_e32 v36, v35
	s_nop 0
	v_fma_f32 v37, -v35, v36, 1.0
	v_fmac_f32_e32 v36, v37, v36
	v_div_scale_f32 v37, vcc, 1.0, v34, 1.0
	v_mul_f32_e32 v58, v37, v36
	v_fma_f32 v59, -v35, v58, v37
	v_fmac_f32_e32 v58, v59, v36
	v_fma_f32 v35, -v35, v58, v37
	v_div_fmas_f32 v35, v35, v36, v58
	v_div_fixup_f32 v58, v35, v34, 1.0
	v_pk_mul_f32 v[66:67], v[66:67], v[58:59] op_sel_hi:[1,0]
	v_pk_mul_f32 v[60:61], v[60:61], v[58:59] op_sel_hi:[1,0]
	v_pk_mul_f32 v[62:63], v[64:65], v[58:59] op_sel_hi:[1,0]
	v_pk_mul_f32 v[64:65], v[38:39], v[58:59] op_sel_hi:[1,0]
	v_pk_mul_f32 v[58:59], v[66:67], v[4:5]
	v_pk_add_f32 v[4:5], v[4:5], -1.0 op_sel_hi:[1,0]
	v_pk_mul_f32 v[34:35], v[60:61], v[6:7]
	v_pk_fma_f32 v[4:5], v[4:5], v[82:83], 1.0 op_sel_hi:[1,1,0]
	v_pk_mul_f32 v[36:37], v[62:63], v[8:9]
	v_pk_mul_f32 v[38:39], v[64:65], v[10:11]
	v_pk_mul_f32 v[68:69], v[68:69], v[4:5]
	v_mov_b32_e32 v4, v216
	v_mov_b32_e32 v5, v217
	v_mov_b32_e32 v6, v218
	v_mov_b32_e32 v7, v219
	v_mov_b32_e32 v8, v220
	v_mov_b32_e32 v9, v221
	v_mov_b32_e32 v10, v222
	v_mov_b32_e32 v11, v223
	v_pk_fma_f32 v[10:11], v[0:1], v[10:11], v[24:25]
	v_lshlrev_b32_e32 v0, 16, v2
	v_and_b32_e32 v1, 0xffff0000, v2
	v_pk_add_f32 v[0:1], v[0:1], v[22:23] neg_lo:[0,1] neg_hi:[0,1]
	v_cvt_pk_bf16_f32 v2, v12, v13
	v_pk_fma_f32 v[4:5], v[0:1], v[4:5], v[22:23]
	v_lshlrev_b32_e32 v0, 16, v3
	v_and_b32_e32 v1, 0xffff0000, v3
	v_pk_add_f32 v[0:1], v[0:1], v[20:21] neg_lo:[0,1] neg_hi:[0,1]
	v_cvt_pk_bf16_f32 v3, v14, v15
	v_pk_fma_f32 v[6:7], v[0:1], v[6:7], v[20:21]
	v_lshlrev_b64 v[20:21], 10, v[56:57]
	v_lshl_or_b32 v20, v44, 1, v20
	v_lshl_add_u64 v[22:23], s[58:59], 0, v[20:21]
	v_cvt_pk_bf16_f32 v0, v16, v17
	v_cvt_pk_bf16_f32 v1, v18, v19
	v_pk_fma_f32 v[8:9], v[70:71], v[8:9], v[28:29]
	global_store_dwordx4 v[22:23], v[0:3], off sc0 sc1 nt
	v_lshl_add_u64 v[12:13], s[60:61], 0, v[20:21]
	s_nop 0
	v_cvt_pk_bf16_f32 v0, v32, v33
	v_cvt_pk_bf16_f32 v1, v30, v31
	v_cvt_pk_bf16_f32 v2, v26, v27
	v_cvt_pk_bf16_f32 v3, v68, v69
	global_store_dwordx4 v[12:13], v[0:3], off sc0 sc1 nt
	v_lshl_add_u64 v[12:13], s[62:63], 0, v[20:21]
	s_nop 0
	v_cvt_pk_bf16_f32 v0, v8, v9
	v_cvt_pk_bf16_f32 v1, v10, v11
	v_cvt_pk_bf16_f32 v2, v4, v5
	v_cvt_pk_bf16_f32 v3, v6, v7
	global_store_dwordx4 v[12:13], v[0:3], off sc0 sc1 nt
	v_lshl_add_u64 v[4:5], s[64:65], 0, v[20:21]
	s_nop 0
	v_cvt_pk_bf16_f32 v0, v60, v61
	v_cvt_pk_bf16_f32 v1, v62, v63
	v_cvt_pk_bf16_f32 v2, v64, v65
	v_cvt_pk_bf16_f32 v3, v66, v67
	global_store_dwordx4 v[4:5], v[0:3], off sc0 sc1 nt
	v_lshl_add_u64 v[4:5], s[66:67], 0, v[20:21]
	s_nop 0
	v_cvt_pk_bf16_f32 v0, v34, v35
	v_cvt_pk_bf16_f32 v1, v36, v37
	v_cvt_pk_bf16_f32 v2, v38, v39
	v_cvt_pk_bf16_f32 v3, v58, v59
	global_store_dwordx4 v[4:5], v[0:3], off sc0 sc1 nt
	s_cbranch_scc0 .LBB0_438
	s_branch .LBB0_522

.LBB0_1395:
	s_waitcnt vmcnt(1)
	v_ashrrev_i32_e32 v26, 1, v4
	v_and_or_b32 v2, v7, 4, v5
	v_ashrrev_i32_e32 v27, 31, v26
	v_lshl_or_b32 v2, v2, 6, v6
	v_lshlrev_b64 v[22:23], 9, v[26:27]
	v_or_b32_e32 v22, v22, v2
	v_lshlrev_b32_e32 v9, 2, v2
	v_lshl_add_u64 v[28:29], v[22:23], 2, s[86:87]
	v_lshlrev_b64 v[22:23], 1, v[22:23]
	global_load_dwordx4 v[10:13], v9, s[16:17]
	global_load_dwordx4 v[14:17], v9, s[18:19]
	global_load_dwordx4 v[18:21], v9, s[20:21]
	v_lshl_add_u64 v[30:31], s[42:43], 0, v[22:23]
	v_lshl_add_u64 v[32:33], s[44:45], 0, v[22:23]
	v_lshl_add_u64 v[34:35], s[46:47], 0, v[22:23]
	v_lshl_add_u64 v[36:37], s[14:15], 0, v[22:23]
	global_load_dwordx4 v[22:25], v[28:29], off
	global_load_dwordx2 v[38:39], v[30:31], off
	global_load_dwordx2 v[40:41], v[32:33], off
	global_load_dwordx2 v[42:43], v[34:35], off
	global_load_dwordx2 v[44:45], v[36:37], off
	v_mad_i64_i32 v[26:27], s[10:11], v26, s2, v[0:1]
	v_lshlrev_b32_e32 v2, 1, v2
	v_lshl_add_u64 v[26:27], v[26:27], 0, v[2:3]
	v_add_u32_e32 v4, s4, v4
	v_cmp_lt_i32_e32 vcc, s3, v4
	s_or_b64 s[8:9], vcc, s[8:9]
	v_add_u32_e32 v7, s0, v7
	s_waitcnt vmcnt(4)
	v_add_f32_e32 v2, v22, v23
	v_add_f32_e32 v2, v2, v24
	s_waitcnt vmcnt(3)
	v_lshlrev_b32_e32 v28, 16, v38
	v_and_b32_e32 v29, 0xffff0000, v38
	s_waitcnt vmcnt(2)
	v_lshlrev_b32_e32 v32, 16, v40
	v_and_b32_e32 v33, 0xffff0000, v40
	v_add_f32_e32 v2, v2, v25
	v_lshlrev_b32_e32 v30, 16, v39
	v_and_b32_e32 v31, 0xffff0000, v39
	v_lshlrev_b32_e32 v34, 16, v41
	v_and_b32_e32 v35, 0xffff0000, v41
	v_pk_mul_f32 v[28:29], v[28:29], v[32:33]
	v_add_f32_dpp v2, v2, v2 quad_perm:[1,0,3,2] row_mask:0xf bank_mask:0xf bound_ctrl:1
	v_pk_mul_f32 v[30:31], v[30:31], v[34:35]
	v_pk_mul_f32 v[10:11], v[10:11], v[28:29]
	v_add_f32_dpp v2, v2, v2 quad_perm:[2,3,0,1] row_mask:0xf bank_mask:0xf bound_ctrl:1
	v_pk_mul_f32 v[12:13], v[12:13], v[30:31]
	v_add_f32_e32 v9, v10, v11
	v_add_f32_dpp v2, v2, v2 row_half_mirror row_mask:0xf bank_mask:0xf bound_ctrl:1
	v_add_f32_e32 v9, v9, v12
	v_add_f32_e32 v9, v13, v9
	v_add_f32_dpp v2, v2, v2 row_ror:8 row_mask:0xf bank_mask:0xf bound_ctrl:1
	v_mul_f32_e32 v2, 0x3c800000, v2
	v_add_f32_dpp v9, v9, v9 quad_perm:[1,0,3,2] row_mask:0xf bank_mask:0xf bound_ctrl:1
	v_pk_add_f32 v[10:11], v[22:23], v[2:3] op_sel_hi:[1,0] neg_lo:[0,1] neg_hi:[0,1]
	v_pk_add_f32 v[12:13], v[24:25], v[2:3] op_sel_hi:[1,0] neg_lo:[0,1] neg_hi:[0,1]
	v_add_f32_dpp v9, v9, v9 quad_perm:[2,3,0,1] row_mask:0xf bank_mask:0xf bound_ctrl:1
	v_pk_mul_f32 v[22:23], v[10:11], v[10:11]
	v_pk_mul_f32 v[24:25], v[12:13], v[12:13]
	v_add_f32_dpp v2, v9, v9 row_half_mirror row_mask:0xf bank_mask:0xf bound_ctrl:1
	v_add_f32_e32 v9, v22, v23
	v_add_f32_e32 v9, v24, v9
	v_add_f32_e32 v9, v25, v9
	s_waitcnt vmcnt(1)
	v_lshlrev_b32_e32 v36, 16, v42
	v_and_b32_e32 v37, 0xffff0000, v42
	v_add_f32_dpp v9, v9, v9 quad_perm:[1,0,3,2] row_mask:0xf bank_mask:0xf bound_ctrl:1
	v_lshlrev_b32_e32 v38, 16, v43
	v_and_b32_e32 v39, 0xffff0000, v43
	v_add_f32_dpp v9, v9, v9 quad_perm:[2,3,0,1] row_mask:0xf bank_mask:0xf bound_ctrl:1
	v_add_f32_dpp v2, v2, v2 row_ror:8 row_mask:0xf bank_mask:0xf bound_ctrl:1
	s_waitcnt vmcnt(0)
	v_lshlrev_b32_e32 v40, 16, v44
	v_add_f32_dpp v9, v9, v9 row_half_mirror row_mask:0xf bank_mask:0xf bound_ctrl:1
	v_and_b32_e32 v41, 0xffff0000, v44
	v_lshlrev_b32_e32 v42, 16, v45
	v_add_f32_dpp v9, v9, v9 row_ror:8 row_mask:0xf bank_mask:0xf bound_ctrl:1
	v_fmamk_f32 v9, v9, 0x3c800000, v8
	v_mul_f32_e32 v22, 0x4b800000, v9
	v_cmp_gt_f32_e32 vcc, s1, v9
	v_and_b32_e32 v43, 0xffff0000, v45
	s_nop 0
	v_cndmask_b32_e32 v9, v9, v22, vcc
	v_rsq_f32_e32 v9, v9
	s_nop 0
	v_mul_f32_e32 v22, 0x45800000, v9
	v_cndmask_b32_e32 v22, v9, v22, vcc
	v_pk_mul_f32 v[10:11], v[10:11], v[22:23] op_sel_hi:[1,0]
	v_pk_mul_f32 v[12:13], v[12:13], v[22:23] op_sel_hi:[1,0]
	v_pk_fma_f32 v[10:11], v[14:15], v[10:11], v[18:19]
	v_pk_fma_f32 v[12:13], v[16:17], v[12:13], v[20:21]
	v_pk_fma_f32 v[10:11], v[2:3], v[36:37], v[10:11] op_sel_hi:[0,1,1]
	v_pk_fma_f32 v[12:13], v[2:3], v[38:39], v[12:13] op_sel_hi:[0,1,1]
	v_pk_mul_f32 v[10:11], v[10:11], v[40:41]
	v_pk_mul_f32 v[12:13], v[12:13], v[42:43]
	v_cvt_pk_bf16_f32 v10, v10, v11
	v_cvt_pk_bf16_f32 v11, v12, v13
	global_store_dwordx2 v[26:27], v[10:11], off offset:1024 sc0 sc1
	s_andn2_b64 exec, exec, s[8:9]
	s_cbranch_execnz .LBB0_1395
